# GEMM K-loops: static priority raise for waves 4-7 (the other half), toggles removed
# baseline (speedup 1.0000x reference)
; template <class Epi, class Sched, bool ALIGN_EPI = false, bool SP2 = false>
; __device__ __forceinline__ void gemm_phase(PG8_LAS unsigned char* lds, const Gemm g, const Sched& S, const Epi& E, const int tid) {
;     ...
;         for (int t = 0; t < nt; t += 2) {
;             const bool last = (t == nt - 2);
.LBB0_279:
	s_cmp_eq_u64 s[12:13], 0
	s_cbranch_scc0 .Lsp_0
	s_setprio 1

; template <class Epi, class Sched, bool ALIGN_EPI = false, bool SP2 = false>
; __device__ __forceinline__ void gemm_phase(PG8_LAS unsigned char* lds, const Gemm g, const Sched& S, const Epi& E, const int tid) {
;     ...
;         for (int t = 0; t < nt; t += 2) {
;             const bool last = (t == nt - 2);
.LBB0_353:
	s_cmp_eq_u64 s[16:17], 0
	s_cbranch_scc0 .Lsp_1
	s_setprio 1

; template <class Epi, class Sched, bool ALIGN_EPI = false, bool SP2 = false>
; __device__ __forceinline__ void gemm_phase(PG8_LAS unsigned char* lds, const Gemm g, const Sched& S, const Epi& E, const int tid) {
;     ...
;         for (int t = 0; t < nt; t += 2) {
;             const bool last = (t == nt - 2);
.LBB0_437:
	s_cmp_eq_u64 s[18:19], 0
	s_cbranch_scc0 .Lsp_2
	s_setprio 1

; template <class Epi, class Sched, bool ALIGN_EPI = false, bool SP2 = false>
; __device__ __forceinline__ void gemm_phase(PG8_LAS unsigned char* lds, const Gemm g, const Sched& S, const Epi& E, const int tid) {
;     ...
;         for (int t = 0; t < nt; t += 2) {
;             const bool last = (t == nt - 2);
.LBB0_923:
	s_cmp_eq_u64 s[20:21], 0
	s_cbranch_scc0 .Lsp_5
	s_setprio 1

; template <class Epi, class Sched, bool ALIGN_EPI = false, bool SP2 = false>
; __device__ __forceinline__ void gemm_phase(PG8_LAS unsigned char* lds, const Gemm g, const Sched& S, const Epi& E, const int tid) {
;     ...
;         for (int t = 0; t < nt; t += 2) {
;             const bool last = (t == nt - 2);
.LBB0_1007:
	s_cmp_eq_u64 s[14:15], 0
	s_cbranch_scc0 .Lsp_6
	s_setprio 1
